# v085 + P10 token mapping: each XCD processes 256 consecutive tokens per round (gridDim==256)
# baseline (speedup 1.0000x reference)
; __device__ __forceinline__ float bf_lo(unsigned u) { return __uint_as_float(u << 16); }
; __device__ __forceinline__ float bf_hi(unsigned u) { return __uint_as_float(u & 0xffff0000u); }
; __global__ void __launch_bounds__(NT, 2) mk_fwd(Args args) {
;     ...
;     if (IN(10)) {
;         const float* fg = args.in[28];
;         for (int tok = gw; tok < MTOK; tok += NGW) {
;             const int b = tok >> 11;
;             f32x2 hf2[16];
; #pragma unroll
;             for (int j = 0; j < 4; ++j) { const u32x4 a = *(const u32x4*)(HB + (size_t)tok * DM + lane * 32 + j * 8);
; #pragma unroll
;                 for (int q = 0; q < 4; ++q) hf2[j * 4 + q] = (f32x2){bf_lo(a[q]), bf_hi(a[q])}; }
;             const int e0 = EIDX[(size_t)tok * 128 + lane], e1 = EIDX[(size_t)tok * 128 + 64 + lane];
;             const float g0 = GATE[(size_t)tok * 128 + lane], g1 = GATE[(size_t)tok * 128 + 64 + lane];
;             const bool hi32 = (lane & 32) != 0, hi16 = (lane & 16) != 0; const int l3 = (lane & 3) << 4;
.LBB0_883:
	s_cmp_lt_i32 s94, 11
	s_cselect_b64 s[2:3], -1, 0
	s_and_b64 s[0:1], s[2:3], s[0:1]
	s_and_b64 s[0:1], s[0:1], s[86:87]
	s_andn2_b64 vcc, exec, s[0:1]
	s_cbranch_vccnz .LBB0_913
	s_cmp_eq_u32 s84, 0x100
	s_cbranch_scc0 .Lp10_nomap
	s_and_b32 s4, s70, 0x38
	s_lshl_b32 s4, s4, 5
	s_lshr_b32 s5, s70, 3
	s_and_b32 s5, s5, 0xf8
	s_and_b32 s70, s70, 7
	s_or_b32 s70, s70, s4
	s_or_b32 s70, s70, s5
.Lp10_nomap:
	s_waitcnt vmcnt(0)
	v_mbcnt_hi_u32_b32 v3, -1, v169
	v_and_b32_e32 v5, 64, v3
	v_xor_b32_e32 v4, 32, v3
	v_add_u32_e32 v6, 64, v5
	v_cmp_lt_i32_e32 vcc, v4, v6
	v_mov_b32_e32 v137, 0
	v_and_b32_e32 v0, 32, v168
	v_cndmask_b32_e32 v4, v3, v4, vcc
	v_cmp_eq_u32_e64 s[0:1], 0, v0
	v_and_b32_e32 v0, 16, v168
	v_mov_b32_e32 v131, v137
	v_lshlrev_b32_e32 v129, 2, v4
	v_xor_b32_e32 v4, 16, v3
	v_cmp_eq_u32_e64 s[2:3], 0, v0
	v_lshlrev_b32_e32 v2, 4, v168
	v_lshl_add_u64 v[0:1], s[92:93], 0, v[130:131]
	s_mov_b64 s[4:5], 0x2a00000
	v_cmp_lt_i32_e32 vcc, v4, v6
	s_add_u32 s6, s92, 0x6a00000
	v_lshl_add_u64 v[96:97], s[80:81], 0, v[136:137]
	v_lshl_add_u64 v[98:99], v[0:1], 0, s[4:5]
	v_cndmask_b32_e32 v3, v3, v4, vcc
	v_and_or_b32 v2, v2, 48, v5
	s_mov_b64 s[4:5], 0x4a00000
	v_lshlrev_b32_e32 v136, 7, v128
	v_and_b32_e32 v148, 60, v128
	s_addc_u32 s7, s93, 0
	v_lshlrev_b32_e32 v146, 2, v3
	v_lshlrev_b32_e32 v147, 2, v2
	v_lshl_add_u64 v[100:101], v[0:1], 0, s[4:5]
	v_lshl_add_u64 v[102:103], s[90:91], 0, v[136:137]
	v_lshl_add_u64 v[104:105], s[88:89], 0, v[136:137]
	v_add_u32_e32 v149, -12, v148
	v_add_u32_e32 v150, -8, v148
	v_add_u32_e32 v151, -4, v148
	s_mov_b32 s11, 0x378e98ab
	s_mov_b32 s13, 0x3b7cd369
	s_mov_b32 s15, 0xbcc618b2
	s_mov_b32 s17, 0x3dda74e4
	s_mov_b32 s19, 0x3f228afd
	s_mov_b32 s21, 0x3e03c728
	s_mov_b32 s23, 0xbfb8aa3b
	s_mov_b32 s25, 0x42ce8ed0
	s_mov_b32 s26, 0xc2b17218
	v_mov_b32_e32 v152, 0x3ba10414
	s_brev_b32 s27, -2
	v_lshlrev_b32_e32 v136, 2, v138
	s_mov_b64 s[8:9], 0xa000
	s_mov_b32 s28, 0xa000
	v_mov_b32_e32 v153, 0x358637bd
	s_mov_b32 s29, 0x800000
	v_mov_b32_e32 v154, 0xb9c68948
	v_mov_b32_e32 v155, 0x7f800000
	s_mov_b32 s50, 0x55555555
	s_mov_b32 s51, 0x55555555
	s_mov_b32 s52, 0x33333333
	s_mov_b32 s53, 0x33333333
	s_mov_b32 s54, 0xf0f0f0f
	s_mov_b32 s55, 0xf0f0f0f
	s_mov_b32 s56, 0xff00ff
	s_mov_b32 s57, 0xff00ff
	s_mov_b32 s58, 0xffff
	s_mov_b32 s59, 0xffff
	s_mov_b32 s60, -1
	s_mov_b32 s61, 0
	global_load_dwordx4 v[186:189], v[104:105], off
	global_load_dwordx4 v[190:193], v[104:105], off offset:16
	global_load_dwordx4 v[194:197], v[104:105], off offset:32
	global_load_dwordx4 v[198:201], v[104:105], off offset:48
	global_load_dwordx4 v[202:205], v[104:105], off offset:64
	global_load_dwordx4 v[206:209], v[104:105], off offset:80
	global_load_dwordx4 v[210:213], v[104:105], off offset:96
	global_load_dwordx4 v[214:217], v[104:105], off offset:112
	s_waitcnt vmcnt(0)
	s_branch .LBB0_886
